# stagger: waves 4-7 sleep ~3k cycles at token-mixer phase entry so the two waves of a SIMD run the same attention loop half a step apart (on top of v10)
# baseline (speedup 1.0000x reference)
; #define LAS __attribute__((address_space(3)))
; __device__ __forceinline__ KArgs kargs() { KArgs p = (KArgs)__builtin_amdgcn_kernarg_segment_ptr(); asm volatile("" : "+s"(p)); return p; }
; __global__ void __launch_bounds__(NTHR, 2) fwd_megakernel(Args A) {
;     ...
;         { KArgs P = kargs(); const bf16* Z = (const bf16*)WSP(WS_R); bf16* YC = (bf16*)WSP(WS_YC);
;           const int tid = threadIdx.x, lane = tid & 63, wave = __builtin_amdgcn_readfirstlane(tid >> 6);
;           const int vb = (G % 8 == 0) ? (int)(blockIdx.x % 8) * (G / 8) + (int)(blockIdx.x / 8) : (int)blockIdx.x;
;           const int gw = vb * NWAVES + wave, NGW = G * NWAVES;
;           LAS unsigned char* vt = lds + wave * WAVE_LDS;
;           if (layer == 0) {
;     ...
;             for (int t = gw; t < 2048; t += NGW) dil_task((const bf16*)WSP(WS_QKV), YC, P->in[11], P->in[12], vt, t, lane);
.LBB0_1486:
	s_or_b64 exec, exec, s[4:5]
	v_readlane_b32 s46, v253, 1
	v_readlane_b32 s47, v253, 2
	s_barrier
	v_readfirstlane_b32 vcc_lo, v218
	s_nop 4
	s_bfe_u32 vcc_lo, vcc_lo, 0x40006
	s_cmp_lt_u32 vcc_lo, 4
	s_cbranch_scc1 .Lstag_skip
	s_sleep 48
.Lstag_skip:
	s_load_dwordx2 s[52:53], s[46:47], 0xb8
	v_readfirstlane_b32 s2, v218
	v_readlane_b32 s4, v252, 29
	v_readlane_b32 s5, v252, 30
	s_waitcnt lgkmcnt(0)
	s_add_u32 s34, s52, 0x15d00000
	s_addc_u32 s35, s53, 0
	s_add_u32 s64, s52, 0x1ad00000
	s_addc_u32 s65, s53, 0
	s_lshr_b32 s6, s2, 6
	v_readlane_b32 s2, v254, 45
	s_add_i32 s62, s2, s6
	s_mul_i32 s2, s6, 0x3800
	s_add_i32 s63, s2, 0
	s_andn2_b64 vcc, exec, s[4:5]
	s_mov_b64 s[4:5], -1
	s_cbranch_vccnz .LBB0_1543
	s_cmpk_gt_i32 s62, 0xfff
	s_cbranch_scc1 .LBB0_1539
	s_add_u32 s2, s52, 0x1cd00000
	s_addc_u32 s22, s53, 0
	s_lshl_b32 s6, s6, 4
	v_readlane_b32 s7, v252, 15
	s_load_dwordx4 s[68:71], s[46:47], 0x78
	s_load_dwordx2 s[4:5], s[46:47], 0x88
	s_add_i32 s23, s7, s6
	s_add_u32 s38, s52, 0x1dd00000
	s_addc_u32 s39, s53, 0
	s_add_u32 s78, s52, 0x1d500080
	s_addc_u32 s79, s53, 0
	s_mov_b32 s26, -1
	s_mov_b32 s24, s62
	s_branch .LBB0_1490
